# rope element peephole: partner select merged with sign select, fmac+mov folded to one fma (121 sites)
# baseline (speedup 1.0000x reference)
.LBB0_264:
	v_mov_b32_e32 v215, v230
	v_mov_b32_e32 v250, v230
	s_nop 1
	v_permlane32_swap_b32_e32 v215, v250
	v_cndmask_b32_e64 v215, v215, -v250, s[10:11]
	s_waitcnt vmcnt(3) lgkmcnt(0)
	v_mul_f32_e32 v215, v149, v215
	v_fma_f32 v230, v230, v148, v215

.LBB0_309:
	v_mov_b32_e32 v215, v230
	v_mov_b32_e32 v250, v230
	s_nop 1
	v_permlane32_swap_b32_e32 v215, v250
	v_cndmask_b32_e64 v215, v215, -v250, s[10:11]
	s_waitcnt vmcnt(3) lgkmcnt(0)
	v_mul_f32_e32 v215, v137, v215
	v_fma_f32 v230, v230, v136, v215

.LBB0_342:
	v_mov_b32_e32 v155, v159
	v_mov_b32_e32 v250, v159
	s_nop 1
	v_permlane32_swap_b32_e32 v155, v250
	v_cndmask_b32_e64 v155, v155, -v250, s[10:11]
	s_waitcnt vmcnt(3) lgkmcnt(0)
	v_mul_f32_e32 v155, v121, v155
	v_fma_f32 v159, v159, v120, v155

.LBB0_354:
	v_mov_b32_e32 v150, v158
	v_mov_b32_e32 v250, v158
	s_nop 1
	v_permlane32_swap_b32_e32 v150, v250
	v_cndmask_b32_e64 v150, v150, -v250, s[10:11]
	s_waitcnt vmcnt(3) lgkmcnt(0)
	v_mul_f32_e32 v150, v121, v150
	v_fma_f32 v158, v158, v120, v150

.LBB0_387:
	v_mov_b32_e32 v143, v147
	v_mov_b32_e32 v250, v147
	s_nop 1
	v_permlane32_swap_b32_e32 v143, v250
	v_cndmask_b32_e64 v143, v143, -v250, s[10:11]
	s_waitcnt vmcnt(3) lgkmcnt(0)
	v_mul_f32_e32 v143, v105, v143
	v_fma_f32 v147, v147, v104, v143

.LBB0_399:
	v_mov_b32_e32 v138, v146
	v_mov_b32_e32 v250, v146
	s_nop 1
	v_permlane32_swap_b32_e32 v138, v250
	v_cndmask_b32_e64 v138, v138, -v250, s[10:11]
	s_waitcnt vmcnt(3) lgkmcnt(0)
	v_mul_f32_e32 v138, v105, v138
	v_fma_f32 v146, v146, v104, v138

.LBB0_432:
	v_mov_b32_e32 v127, v131
	v_mov_b32_e32 v250, v131
	s_nop 1
	v_permlane32_swap_b32_e32 v127, v250
	v_cndmask_b32_e64 v127, v127, -v250, s[10:11]
	s_waitcnt vmcnt(3) lgkmcnt(0)
	v_mul_f32_e32 v127, v89, v127
	v_fma_f32 v131, v131, v88, v127

.LBB0_445:
	v_mov_b32_e32 v124, v132
	v_mov_b32_e32 v250, v132
	s_nop 1
	v_permlane32_swap_b32_e32 v124, v250
	v_cndmask_b32_e64 v124, v124, -v250, s[10:11]
	s_waitcnt vmcnt(3) lgkmcnt(0)
	v_mul_f32_e32 v124, v89, v124
	v_fma_f32 v132, v132, v88, v124

.LBB0_478:
	v_mov_b32_e32 v111, v115
	v_mov_b32_e32 v250, v115
	s_nop 1
	v_permlane32_swap_b32_e32 v111, v250
	v_cndmask_b32_e64 v111, v111, -v250, s[10:11]
	s_waitcnt vmcnt(3) lgkmcnt(0)
	v_mul_f32_e32 v111, v73, v111
	v_fma_f32 v115, v115, v72, v111

.LBB0_491:
	v_mov_b32_e32 v108, v116
	v_mov_b32_e32 v250, v116
	s_nop 1
	v_permlane32_swap_b32_e32 v108, v250
	v_cndmask_b32_e64 v108, v108, -v250, s[10:11]
	s_waitcnt vmcnt(3) lgkmcnt(0)
	v_mul_f32_e32 v108, v73, v108
	v_fma_f32 v116, v116, v72, v108

.LBB0_524:
	v_mov_b32_e32 v95, v99
	v_mov_b32_e32 v250, v99
	s_nop 1
	v_permlane32_swap_b32_e32 v95, v250
	v_cndmask_b32_e64 v95, v95, -v250, s[10:11]
	s_waitcnt vmcnt(3) lgkmcnt(0)
	v_mul_f32_e32 v95, v57, v95
	v_fma_f32 v99, v99, v56, v95

.LBB0_537:
	v_mov_b32_e32 v92, v100
	v_mov_b32_e32 v250, v100
	s_nop 1
	v_permlane32_swap_b32_e32 v92, v250
	v_cndmask_b32_e64 v92, v92, -v250, s[10:11]
	s_waitcnt vmcnt(3) lgkmcnt(0)
	v_mul_f32_e32 v92, v57, v92
	v_fma_f32 v100, v100, v56, v92

.LBB0_575:
	v_mov_b32_e32 v37, v41
	v_mov_b32_e32 v250, v41
	s_nop 1
	v_permlane32_swap_b32_e32 v37, v250
	v_cndmask_b32_e64 v37, v37, -v250, s[10:11]
	s_waitcnt vmcnt(3) lgkmcnt(0)
	v_mul_f32_e32 v37, v57, v37
	v_fma_f32 v41, v41, v56, v37

.LBB0_588:
	v_mov_b32_e32 v24, v25
	v_mov_b32_e32 v250, v25
	s_nop 1
	v_permlane32_swap_b32_e32 v24, v250
	v_cndmask_b32_e64 v24, v24, -v250, s[10:11]
	s_waitcnt vmcnt(3) lgkmcnt(0)
	v_mul_f32_e32 v24, v57, v24
	v_fma_f32 v25, v25, v56, v24

.LBB0_599:
	v_mov_b32_e32 v205, v0
	v_mov_b32_e32 v250, v0
	s_nop 1
	v_permlane32_swap_b32_e32 v205, v250
	v_cndmask_b32_e64 v205, v205, -v250, s[10:11]
	s_waitcnt lgkmcnt(0)
	v_mul_f32_e32 v205, v159, v205
	v_fma_f32 v0, v0, v158, v205
	v_mul_f32_e32 v205, v163, v216
	s_and_b64 vcc, exec, s[0:1]
	v_mul_f32_e32 v205, v39, v205
	s_cbranch_vccnz .LBB0_246
.LBB0_600:
	v_mov_b32_e32 v206, v205
	v_mov_b32_e32 v250, v205
	s_nop 1
	v_permlane32_swap_b32_e32 v206, v250
	v_cndmask_b32_e64 v206, v206, -v250, s[10:11]
	s_waitcnt lgkmcnt(0)
	v_mul_f32_e32 v206, v161, v206
	v_fma_f32 v205, v205, v160, v206
	v_mul_f32_e32 v206, v164, v216
	s_and_b64 vcc, exec, s[0:1]
	v_mul_f32_e32 v206, v40, v206
	s_cbranch_vccnz .LBB0_247
.LBB0_601:
	v_mov_b32_e32 v207, v206
	v_mov_b32_e32 v250, v206
	s_nop 1
	v_permlane32_swap_b32_e32 v207, v250
	v_cndmask_b32_e64 v207, v207, -v250, s[10:11]
	s_waitcnt lgkmcnt(0)
	v_mul_f32_e32 v207, v155, v207
	v_fma_f32 v206, v206, v154, v207
	v_mul_f32_e32 v207, v165, v216
	s_and_b64 vcc, exec, s[0:1]
	v_mul_f32_e32 v207, v41, v207
	s_cbranch_vccnz .LBB0_248
.LBB0_602:
	v_mov_b32_e32 v217, v207
	v_mov_b32_e32 v250, v207
	s_nop 1
	v_permlane32_swap_b32_e32 v217, v250
	v_cndmask_b32_e64 v217, v217, -v250, s[10:11]
	s_waitcnt lgkmcnt(0)
	v_mul_f32_e32 v217, v157, v217
	v_fma_f32 v207, v207, v156, v217
	v_mul_f32_e32 v217, v142, v216
	s_and_b64 vcc, exec, s[0:1]
	v_mul_f32_e32 v219, v34, v217
	s_cbranch_vccnz .LBB0_249
.LBB0_603:
	v_mov_b32_e32 v217, v219
	v_mov_b32_e32 v250, v219
	s_nop 1
	v_permlane32_swap_b32_e32 v217, v250
	v_cndmask_b32_e64 v217, v217, -v250, s[10:11]
	s_waitcnt lgkmcnt(0)
	v_mul_f32_e32 v217, v151, v217
	v_fma_f32 v219, v219, v150, v217
	v_mul_f32_e32 v217, v143, v216
	s_and_b64 vcc, exec, s[0:1]
	v_mul_f32_e32 v218, v35, v217
	s_cbranch_vccnz .LBB0_250
.LBB0_604:
	v_mov_b32_e32 v217, v218
	v_mov_b32_e32 v250, v218
	s_nop 1
	v_permlane32_swap_b32_e32 v217, v250
	v_cndmask_b32_e64 v217, v217, -v250, s[10:11]
	s_waitcnt lgkmcnt(0)
	v_mul_f32_e32 v217, v153, v217
	v_fma_f32 v218, v218, v152, v217
	v_mul_f32_e32 v217, v144, v216
	s_and_b64 vcc, exec, s[0:1]
	v_mul_f32_e32 v217, v36, v217
	s_cbranch_vccnz .LBB0_251
.LBB0_605:
	v_mov_b32_e32 v226, v217
	v_mov_b32_e32 v250, v217
	s_nop 1
	v_permlane32_swap_b32_e32 v226, v250
	v_cndmask_b32_e64 v226, v226, -v250, s[10:11]
	s_waitcnt lgkmcnt(0)
	v_mul_f32_e32 v226, v147, v226
	v_fma_f32 v217, v217, v146, v226
	v_mul_f32_e32 v226, v145, v216
	s_and_b64 vcc, exec, s[0:1]
	v_mul_f32_e32 v231, v37, v226
	s_cbranch_vccz .LBB0_252
	s_branch .LBB0_253

.LBB0_609:
	v_mov_b32_e32 v217, v0
	v_mov_b32_e32 v250, v0
	s_nop 1
	v_permlane32_swap_b32_e32 v217, v250
	v_cndmask_b32_e64 v217, v217, -v250, s[10:11]
	s_waitcnt vmcnt(0) lgkmcnt(0)
	v_mul_f32_e32 v217, v159, v217
	v_fma_f32 v0, v0, v158, v217
	v_mul_f32_e32 v217, v139, v216
	s_and_b64 vcc, exec, s[0:1]
	v_mul_f32_e32 v217, v27, v217
	s_cbranch_vccnz .LBB0_258
.LBB0_610:
	v_mov_b32_e32 v218, v217
	v_mov_b32_e32 v250, v217
	s_nop 1
	v_permlane32_swap_b32_e32 v218, v250
	v_cndmask_b32_e64 v218, v218, -v250, s[10:11]
	s_waitcnt vmcnt(0) lgkmcnt(0)
	v_mul_f32_e32 v218, v161, v218
	v_fma_f32 v217, v217, v160, v218
	v_mul_f32_e32 v218, v140, v216
	s_and_b64 vcc, exec, s[0:1]
	v_mul_f32_e32 v218, v28, v218
	s_cbranch_vccnz .LBB0_259
.LBB0_611:
	v_mov_b32_e32 v219, v218
	v_mov_b32_e32 v250, v218
	s_nop 1
	v_permlane32_swap_b32_e32 v219, v250
	v_cndmask_b32_e64 v219, v219, -v250, s[10:11]
	s_waitcnt vmcnt(1) lgkmcnt(0)
	v_mul_f32_e32 v219, v155, v219
	v_fma_f32 v218, v218, v154, v219
	v_mul_f32_e32 v219, v141, v216
	s_and_b64 vcc, exec, s[0:1]
	v_mul_f32_e32 v219, v29, v219
	s_cbranch_vccnz .LBB0_260
.LBB0_612:
	v_mov_b32_e32 v226, v219
	v_mov_b32_e32 v250, v219
	s_nop 1
	v_permlane32_swap_b32_e32 v226, v250
	v_cndmask_b32_e64 v226, v226, -v250, s[10:11]
	s_waitcnt vmcnt(1) lgkmcnt(0)
	v_mul_f32_e32 v226, v157, v226
	v_fma_f32 v219, v219, v156, v226
	v_mul_f32_e32 v226, v134, v216
	s_and_b64 vcc, exec, s[0:1]
	v_mul_f32_e32 v227, v22, v226
	s_cbranch_vccnz .LBB0_261
.LBB0_613:
	v_mov_b32_e32 v226, v227
	v_mov_b32_e32 v250, v227
	s_nop 1
	v_permlane32_swap_b32_e32 v226, v250
	v_cndmask_b32_e64 v226, v226, -v250, s[10:11]
	s_waitcnt vmcnt(2) lgkmcnt(0)
	v_mul_f32_e32 v226, v151, v226
	v_fma_f32 v227, v227, v150, v226
	v_mul_f32_e32 v226, v135, v216
	s_and_b64 vcc, exec, s[0:1]
	v_mul_f32_e32 v228, v23, v226
	s_cbranch_vccnz .LBB0_262
.LBB0_614:
	v_mov_b32_e32 v226, v228
	v_mov_b32_e32 v250, v228
	s_nop 1
	v_permlane32_swap_b32_e32 v226, v250
	v_cndmask_b32_e64 v226, v226, -v250, s[10:11]
	s_waitcnt vmcnt(2) lgkmcnt(0)
	v_mul_f32_e32 v226, v153, v226
	v_fma_f32 v228, v228, v152, v226
	v_mul_f32_e32 v226, v136, v216
	s_and_b64 vcc, exec, s[0:1]
	v_mul_f32_e32 v229, v24, v226
	s_cbranch_vccnz .LBB0_263

.LBB0_621:
	v_mov_b32_e32 v205, v0
	v_mov_b32_e32 v250, v0
	s_nop 1
	v_permlane32_swap_b32_e32 v205, v250
	v_cndmask_b32_e64 v205, v205, -v250, s[10:11]
	s_waitcnt vmcnt(0) lgkmcnt(0)
	v_mul_f32_e32 v205, v163, v205
	v_fma_f32 v0, v0, v162, v205
	v_mul_f32_e32 v205, v131, v216
	s_and_b64 vcc, exec, s[0:1]
	v_mul_f32_e32 v205, v39, v205
	s_cbranch_vccnz .LBB0_291
.LBB0_622:
	v_mov_b32_e32 v206, v205
	v_mov_b32_e32 v250, v205
	s_nop 1
	v_permlane32_swap_b32_e32 v206, v250
	v_cndmask_b32_e64 v206, v206, -v250, s[10:11]
	s_waitcnt vmcnt(0) lgkmcnt(0)
	v_mul_f32_e32 v206, v165, v206
	v_fma_f32 v205, v205, v164, v206
	v_mul_f32_e32 v206, v132, v216
	s_and_b64 vcc, exec, s[0:1]
	v_mul_f32_e32 v206, v40, v206
	s_cbranch_vccnz .LBB0_292
.LBB0_623:
	v_mov_b32_e32 v207, v206
	v_mov_b32_e32 v250, v206
	s_nop 1
	v_permlane32_swap_b32_e32 v207, v250
	v_cndmask_b32_e64 v207, v207, -v250, s[10:11]
	s_waitcnt vmcnt(1) lgkmcnt(0)
	v_mul_f32_e32 v207, v143, v207
	v_fma_f32 v206, v206, v142, v207
	v_mul_f32_e32 v207, v133, v216
	s_and_b64 vcc, exec, s[0:1]
	v_mul_f32_e32 v207, v41, v207
	s_cbranch_vccnz .LBB0_293
.LBB0_624:
	v_mov_b32_e32 v217, v207
	v_mov_b32_e32 v250, v207
	s_nop 1
	v_permlane32_swap_b32_e32 v217, v250
	v_cndmask_b32_e64 v217, v217, -v250, s[10:11]
	s_waitcnt vmcnt(1) lgkmcnt(0)
	v_mul_f32_e32 v217, v145, v217
	v_fma_f32 v207, v207, v144, v217
	v_mul_f32_e32 v217, v126, v216
	s_and_b64 vcc, exec, s[0:1]
	v_mul_f32_e32 v219, v34, v217
	s_cbranch_vccnz .LBB0_294
.LBB0_625:
	v_mov_b32_e32 v217, v219
	v_mov_b32_e32 v250, v219
	s_nop 1
	v_permlane32_swap_b32_e32 v217, v250
	v_cndmask_b32_e64 v217, v217, -v250, s[10:11]
	s_waitcnt vmcnt(2) lgkmcnt(0)
	v_mul_f32_e32 v217, v139, v217
	v_fma_f32 v219, v219, v138, v217
	v_mul_f32_e32 v217, v127, v216
	s_and_b64 vcc, exec, s[0:1]
	v_mul_f32_e32 v218, v35, v217
	s_cbranch_vccnz .LBB0_295
.LBB0_626:
	v_mov_b32_e32 v217, v218
	v_mov_b32_e32 v250, v218
	s_nop 1
	v_permlane32_swap_b32_e32 v217, v250
	v_cndmask_b32_e64 v217, v217, -v250, s[10:11]
	s_waitcnt vmcnt(2) lgkmcnt(0)
	v_mul_f32_e32 v217, v141, v217
	v_fma_f32 v218, v218, v140, v217
	v_mul_f32_e32 v217, v128, v216
	s_and_b64 vcc, exec, s[0:1]
	v_mul_f32_e32 v217, v36, v217
	s_cbranch_vccnz .LBB0_296
.LBB0_627:
	v_mov_b32_e32 v226, v217
	v_mov_b32_e32 v250, v217
	s_nop 1
	v_permlane32_swap_b32_e32 v226, v250
	v_cndmask_b32_e64 v226, v226, -v250, s[10:11]
	s_waitcnt vmcnt(3) lgkmcnt(0)
	v_mul_f32_e32 v226, v135, v226
	v_fma_f32 v217, v217, v134, v226
	v_mul_f32_e32 v226, v129, v216
	s_and_b64 vcc, exec, s[0:1]
	v_mul_f32_e32 v231, v37, v226
	s_cbranch_vccz .LBB0_297
	s_branch .LBB0_298

.LBB0_631:
	v_mov_b32_e32 v217, v0
	v_mov_b32_e32 v250, v0
	s_nop 1
	v_permlane32_swap_b32_e32 v217, v250
	v_cndmask_b32_e64 v217, v217, -v250, s[10:11]
	s_waitcnt vmcnt(0) lgkmcnt(0)
	v_mul_f32_e32 v217, v163, v217
	v_fma_f32 v0, v0, v162, v217
	v_mul_f32_e32 v217, v123, v216
	s_and_b64 vcc, exec, s[0:1]
	v_mul_f32_e32 v217, v27, v217
	s_cbranch_vccnz .LBB0_303
.LBB0_632:
	v_mov_b32_e32 v218, v217
	v_mov_b32_e32 v250, v217
	s_nop 1
	v_permlane32_swap_b32_e32 v218, v250
	v_cndmask_b32_e64 v218, v218, -v250, s[10:11]
	s_waitcnt vmcnt(0) lgkmcnt(0)
	v_mul_f32_e32 v218, v165, v218
	v_fma_f32 v217, v217, v164, v218
	v_mul_f32_e32 v218, v124, v216
	s_and_b64 vcc, exec, s[0:1]
	v_mul_f32_e32 v218, v28, v218
	s_cbranch_vccnz .LBB0_304
.LBB0_633:
	v_mov_b32_e32 v219, v218
	v_mov_b32_e32 v250, v218
	s_nop 1
	v_permlane32_swap_b32_e32 v219, v250
	v_cndmask_b32_e64 v219, v219, -v250, s[10:11]
	s_waitcnt vmcnt(1) lgkmcnt(0)
	v_mul_f32_e32 v219, v143, v219
	v_fma_f32 v218, v218, v142, v219
	v_mul_f32_e32 v219, v125, v216
	s_and_b64 vcc, exec, s[0:1]
	v_mul_f32_e32 v219, v29, v219
	s_cbranch_vccnz .LBB0_305
.LBB0_634:
	v_mov_b32_e32 v226, v219
	v_mov_b32_e32 v250, v219
	s_nop 1
	v_permlane32_swap_b32_e32 v226, v250
	v_cndmask_b32_e64 v226, v226, -v250, s[10:11]
	s_waitcnt vmcnt(1) lgkmcnt(0)
	v_mul_f32_e32 v226, v145, v226
	v_fma_f32 v219, v219, v144, v226
	v_mul_f32_e32 v226, v118, v216
	s_and_b64 vcc, exec, s[0:1]
	v_mul_f32_e32 v227, v22, v226
	s_cbranch_vccnz .LBB0_306
.LBB0_635:
	v_mov_b32_e32 v226, v227
	v_mov_b32_e32 v250, v227
	s_nop 1
	v_permlane32_swap_b32_e32 v226, v250
	v_cndmask_b32_e64 v226, v226, -v250, s[10:11]
	s_waitcnt vmcnt(2) lgkmcnt(0)
	v_mul_f32_e32 v226, v139, v226
	v_fma_f32 v227, v227, v138, v226
	v_mul_f32_e32 v226, v119, v216
	s_and_b64 vcc, exec, s[0:1]
	v_mul_f32_e32 v228, v23, v226
	s_cbranch_vccnz .LBB0_307
.LBB0_636:
	v_mov_b32_e32 v226, v228
	v_mov_b32_e32 v250, v228
	s_nop 1
	v_permlane32_swap_b32_e32 v226, v250
	v_cndmask_b32_e64 v226, v226, -v250, s[10:11]
	s_waitcnt vmcnt(2) lgkmcnt(0)
	v_mul_f32_e32 v226, v141, v226
	v_fma_f32 v228, v228, v140, v226
	v_mul_f32_e32 v226, v120, v216
	s_and_b64 vcc, exec, s[0:1]
	v_mul_f32_e32 v229, v24, v226
	s_cbranch_vccnz .LBB0_308

.LBB0_643:
	v_mov_b32_e32 v147, v0
	v_mov_b32_e32 v250, v0
	s_nop 1
	v_permlane32_swap_b32_e32 v147, v250
	v_cndmask_b32_e64 v147, v147, -v250, s[10:11]
	s_waitcnt vmcnt(0) lgkmcnt(0)
	v_mul_f32_e32 v147, v131, v147
	v_fma_f32 v0, v0, v130, v147
	v_mul_f32_e32 v147, v115, v151
	s_and_b64 vcc, exec, s[0:1]
	v_mul_f32_e32 v147, v39, v147
	s_cbranch_vccnz .LBB0_336
.LBB0_644:
	v_mov_b32_e32 v148, v147
	v_mov_b32_e32 v250, v147
	s_nop 1
	v_permlane32_swap_b32_e32 v148, v250
	v_cndmask_b32_e64 v148, v148, -v250, s[10:11]
	s_waitcnt vmcnt(0) lgkmcnt(0)
	v_mul_f32_e32 v148, v133, v148
	v_fma_f32 v147, v147, v132, v148
	v_mul_f32_e32 v148, v116, v151
	s_and_b64 vcc, exec, s[0:1]
	v_mul_f32_e32 v148, v40, v148
	s_cbranch_vccnz .LBB0_337
.LBB0_645:
	v_mov_b32_e32 v149, v148
	v_mov_b32_e32 v250, v148
	s_nop 1
	v_permlane32_swap_b32_e32 v149, v250
	v_cndmask_b32_e64 v149, v149, -v250, s[10:11]
	s_waitcnt vmcnt(1) lgkmcnt(0)
	v_mul_f32_e32 v149, v127, v149
	v_fma_f32 v148, v148, v126, v149
	v_mul_f32_e32 v149, v117, v151
	s_and_b64 vcc, exec, s[0:1]
	v_mul_f32_e32 v149, v41, v149
	s_cbranch_vccnz .LBB0_338
.LBB0_646:
	v_mov_b32_e32 v152, v149
	v_mov_b32_e32 v250, v149
	s_nop 1
	v_permlane32_swap_b32_e32 v152, v250
	v_cndmask_b32_e64 v152, v152, -v250, s[10:11]
	s_waitcnt vmcnt(1) lgkmcnt(0)
	v_mul_f32_e32 v152, v129, v152
	v_fma_f32 v149, v149, v128, v152
	v_mul_f32_e32 v152, v110, v151
	s_and_b64 vcc, exec, s[0:1]
	v_mul_f32_e32 v154, v34, v152
	s_cbranch_vccnz .LBB0_339
.LBB0_647:
	v_mov_b32_e32 v152, v154
	v_mov_b32_e32 v250, v154
	s_nop 1
	v_permlane32_swap_b32_e32 v152, v250
	v_cndmask_b32_e64 v152, v152, -v250, s[10:11]
	s_waitcnt vmcnt(2) lgkmcnt(0)
	v_mul_f32_e32 v152, v123, v152
	v_fma_f32 v154, v154, v122, v152
	v_mul_f32_e32 v152, v111, v151
	s_and_b64 vcc, exec, s[0:1]
	v_mul_f32_e32 v153, v35, v152
	s_cbranch_vccnz .LBB0_340
.LBB0_648:
	v_mov_b32_e32 v152, v153
	v_mov_b32_e32 v250, v153
	s_nop 1
	v_permlane32_swap_b32_e32 v152, v250
	v_cndmask_b32_e64 v152, v152, -v250, s[10:11]
	s_waitcnt vmcnt(2) lgkmcnt(0)
	v_mul_f32_e32 v152, v125, v152
	v_fma_f32 v153, v153, v124, v152
	v_mul_f32_e32 v152, v112, v151
	s_and_b64 vcc, exec, s[0:1]
	v_mul_f32_e32 v152, v36, v152
	s_cbranch_vccnz .LBB0_341
.LBB0_649:
	v_mov_b32_e32 v155, v152
	v_mov_b32_e32 v250, v152
	s_nop 1
	v_permlane32_swap_b32_e32 v155, v250
	v_cndmask_b32_e64 v155, v155, -v250, s[10:11]
	s_waitcnt vmcnt(3) lgkmcnt(0)
	v_mul_f32_e32 v155, v119, v155
	v_fma_f32 v152, v152, v118, v155
	v_mul_f32_e32 v155, v113, v151
	s_and_b64 vcc, exec, s[0:1]
	v_mul_f32_e32 v159, v37, v155
	s_cbranch_vccz .LBB0_342
	s_branch .LBB0_343

.LBB0_653:
	v_mov_b32_e32 v152, v0
	v_mov_b32_e32 v250, v0
	s_nop 1
	v_permlane32_swap_b32_e32 v152, v250
	v_cndmask_b32_e64 v152, v152, -v250, s[10:11]
	s_waitcnt vmcnt(0) lgkmcnt(0)
	v_mul_f32_e32 v152, v131, v152
	v_fma_f32 v0, v0, v130, v152
	v_mul_f32_e32 v152, v107, v151
	s_and_b64 vcc, exec, s[0:1]
	v_mul_f32_e32 v152, v27, v152
	s_cbranch_vccnz .LBB0_348
.LBB0_654:
	v_mov_b32_e32 v153, v152
	v_mov_b32_e32 v250, v152
	s_nop 1
	v_permlane32_swap_b32_e32 v153, v250
	v_cndmask_b32_e64 v153, v153, -v250, s[10:11]
	s_waitcnt vmcnt(0) lgkmcnt(0)
	v_mul_f32_e32 v153, v133, v153
	v_fma_f32 v152, v152, v132, v153
	v_mul_f32_e32 v153, v108, v151
	s_and_b64 vcc, exec, s[0:1]
	v_mul_f32_e32 v153, v28, v153
	s_cbranch_vccnz .LBB0_349
.LBB0_655:
	v_mov_b32_e32 v154, v153
	v_mov_b32_e32 v250, v153
	s_nop 1
	v_permlane32_swap_b32_e32 v154, v250
	v_cndmask_b32_e64 v154, v154, -v250, s[10:11]
	s_waitcnt vmcnt(1) lgkmcnt(0)
	v_mul_f32_e32 v154, v127, v154
	v_fma_f32 v153, v153, v126, v154
	v_mul_f32_e32 v154, v109, v151
	s_and_b64 vcc, exec, s[0:1]
	v_mul_f32_e32 v154, v29, v154
	s_cbranch_vccnz .LBB0_350
.LBB0_656:
	v_mov_b32_e32 v155, v154
	v_mov_b32_e32 v250, v154
	s_nop 1
	v_permlane32_swap_b32_e32 v155, v250
	v_cndmask_b32_e64 v155, v155, -v250, s[10:11]
	s_waitcnt vmcnt(1) lgkmcnt(0)
	v_mul_f32_e32 v155, v129, v155
	v_fma_f32 v154, v154, v128, v155
	v_mul_f32_e32 v155, v102, v151
	s_and_b64 vcc, exec, s[0:1]
	v_mul_f32_e32 v155, v22, v155
	s_cbranch_vccnz .LBB0_351
.LBB0_657:
	v_mov_b32_e32 v156, v155
	v_mov_b32_e32 v250, v155
	s_nop 1
	v_permlane32_swap_b32_e32 v156, v250
	v_cndmask_b32_e64 v156, v156, -v250, s[10:11]
	s_waitcnt vmcnt(2) lgkmcnt(0)
	v_mul_f32_e32 v156, v123, v156
	v_fma_f32 v155, v155, v122, v156
	v_mul_f32_e32 v156, v103, v151
	s_and_b64 vcc, exec, s[0:1]
	v_mul_f32_e32 v156, v23, v156
	s_cbranch_vccnz .LBB0_352
.LBB0_658:
	v_mov_b32_e32 v157, v156
	v_mov_b32_e32 v250, v156
	s_nop 1
	v_permlane32_swap_b32_e32 v157, v250
	v_cndmask_b32_e64 v157, v157, -v250, s[10:11]
	s_waitcnt vmcnt(2) lgkmcnt(0)
	v_mul_f32_e32 v157, v125, v157
	v_fma_f32 v156, v156, v124, v157
	v_mul_f32_e32 v157, v104, v151
	s_and_b64 vcc, exec, s[0:1]
	v_mul_f32_e32 v157, v24, v157
	s_cbranch_vccnz .LBB0_353
.LBB0_659:
	v_mov_b32_e32 v158, v157
	v_mov_b32_e32 v250, v157
	s_nop 1
	v_permlane32_swap_b32_e32 v158, v250
	v_cndmask_b32_e64 v158, v158, -v250, s[10:11]
	s_waitcnt vmcnt(3) lgkmcnt(0)
	v_mul_f32_e32 v158, v119, v158
	v_fma_f32 v157, v157, v118, v158
	v_mul_f32_e32 v151, v105, v151
	s_and_b64 vcc, exec, s[0:1]
	v_mul_f32_e32 v158, v25, v151
	s_cbranch_vccz .LBB0_354
	s_branch .LBB0_355

.LBB0_665:
	v_mov_b32_e32 v135, v0
	v_mov_b32_e32 v250, v0
	s_nop 1
	v_permlane32_swap_b32_e32 v135, v250
	v_cndmask_b32_e64 v135, v135, -v250, s[10:11]
	s_waitcnt vmcnt(0) lgkmcnt(0)
	v_mul_f32_e32 v135, v115, v135
	v_fma_f32 v0, v0, v114, v135
	v_mul_f32_e32 v135, v99, v139
	s_and_b64 vcc, exec, s[0:1]
	v_mul_f32_e32 v135, v39, v135
	s_cbranch_vccnz .LBB0_381
.LBB0_666:
	v_mov_b32_e32 v136, v135
	v_mov_b32_e32 v250, v135
	s_nop 1
	v_permlane32_swap_b32_e32 v136, v250
	v_cndmask_b32_e64 v136, v136, -v250, s[10:11]
	s_waitcnt vmcnt(0) lgkmcnt(0)
	v_mul_f32_e32 v136, v117, v136
	v_fma_f32 v135, v135, v116, v136
	v_mul_f32_e32 v136, v100, v139
	s_and_b64 vcc, exec, s[0:1]
	v_mul_f32_e32 v136, v40, v136
	s_cbranch_vccnz .LBB0_382
.LBB0_667:
	v_mov_b32_e32 v137, v136
	v_mov_b32_e32 v250, v136
	s_nop 1
	v_permlane32_swap_b32_e32 v137, v250
	v_cndmask_b32_e64 v137, v137, -v250, s[10:11]
	s_waitcnt vmcnt(1) lgkmcnt(0)
	v_mul_f32_e32 v137, v111, v137
	v_fma_f32 v136, v136, v110, v137
	v_mul_f32_e32 v137, v101, v139
	s_and_b64 vcc, exec, s[0:1]
	v_mul_f32_e32 v137, v41, v137
	s_cbranch_vccnz .LBB0_383
.LBB0_668:
	v_mov_b32_e32 v140, v137
	v_mov_b32_e32 v250, v137
	s_nop 1
	v_permlane32_swap_b32_e32 v140, v250
	v_cndmask_b32_e64 v140, v140, -v250, s[10:11]
	s_waitcnt vmcnt(1) lgkmcnt(0)
	v_mul_f32_e32 v140, v113, v140
	v_fma_f32 v137, v137, v112, v140
	v_mul_f32_e32 v140, v94, v139
	s_and_b64 vcc, exec, s[0:1]
	v_mul_f32_e32 v142, v34, v140
	s_cbranch_vccnz .LBB0_384
.LBB0_669:
	v_mov_b32_e32 v140, v142
	v_mov_b32_e32 v250, v142
	s_nop 1
	v_permlane32_swap_b32_e32 v140, v250
	v_cndmask_b32_e64 v140, v140, -v250, s[10:11]
	s_waitcnt vmcnt(2) lgkmcnt(0)
	v_mul_f32_e32 v140, v107, v140
	v_fma_f32 v142, v142, v106, v140
	v_mul_f32_e32 v140, v95, v139
	s_and_b64 vcc, exec, s[0:1]
	v_mul_f32_e32 v141, v35, v140
	s_cbranch_vccnz .LBB0_385
.LBB0_670:
	v_mov_b32_e32 v140, v141
	v_mov_b32_e32 v250, v141
	s_nop 1
	v_permlane32_swap_b32_e32 v140, v250
	v_cndmask_b32_e64 v140, v140, -v250, s[10:11]
	s_waitcnt vmcnt(2) lgkmcnt(0)
	v_mul_f32_e32 v140, v109, v140
	v_fma_f32 v141, v141, v108, v140
	v_mul_f32_e32 v140, v96, v139
	s_and_b64 vcc, exec, s[0:1]
	v_mul_f32_e32 v140, v36, v140
	s_cbranch_vccnz .LBB0_386
.LBB0_671:
	v_mov_b32_e32 v143, v140
	v_mov_b32_e32 v250, v140
	s_nop 1
	v_permlane32_swap_b32_e32 v143, v250
	v_cndmask_b32_e64 v143, v143, -v250, s[10:11]
	s_waitcnt vmcnt(3) lgkmcnt(0)
	v_mul_f32_e32 v143, v103, v143
	v_fma_f32 v140, v140, v102, v143
	v_mul_f32_e32 v143, v97, v139
	s_and_b64 vcc, exec, s[0:1]
	v_mul_f32_e32 v147, v37, v143
	s_cbranch_vccz .LBB0_387
	s_branch .LBB0_388

.LBB0_675:
	v_mov_b32_e32 v140, v0
	v_mov_b32_e32 v250, v0
	s_nop 1
	v_permlane32_swap_b32_e32 v140, v250
	v_cndmask_b32_e64 v140, v140, -v250, s[10:11]
	s_waitcnt vmcnt(0) lgkmcnt(0)
	v_mul_f32_e32 v140, v115, v140
	v_fma_f32 v0, v0, v114, v140
	v_mul_f32_e32 v140, v91, v139
	s_and_b64 vcc, exec, s[0:1]
	v_mul_f32_e32 v140, v27, v140
	s_cbranch_vccnz .LBB0_393
.LBB0_676:
	v_mov_b32_e32 v141, v140
	v_mov_b32_e32 v250, v140
	s_nop 1
	v_permlane32_swap_b32_e32 v141, v250
	v_cndmask_b32_e64 v141, v141, -v250, s[10:11]
	s_waitcnt vmcnt(0) lgkmcnt(0)
	v_mul_f32_e32 v141, v117, v141
	v_fma_f32 v140, v140, v116, v141
	v_mul_f32_e32 v141, v92, v139
	s_and_b64 vcc, exec, s[0:1]
	v_mul_f32_e32 v141, v28, v141
	s_cbranch_vccnz .LBB0_394
.LBB0_677:
	v_mov_b32_e32 v142, v141
	v_mov_b32_e32 v250, v141
	s_nop 1
	v_permlane32_swap_b32_e32 v142, v250
	v_cndmask_b32_e64 v142, v142, -v250, s[10:11]
	s_waitcnt vmcnt(1) lgkmcnt(0)
	v_mul_f32_e32 v142, v111, v142
	v_fma_f32 v141, v141, v110, v142
	v_mul_f32_e32 v142, v93, v139
	s_and_b64 vcc, exec, s[0:1]
	v_mul_f32_e32 v142, v29, v142
	s_cbranch_vccnz .LBB0_395
.LBB0_678:
	v_mov_b32_e32 v143, v142
	v_mov_b32_e32 v250, v142
	s_nop 1
	v_permlane32_swap_b32_e32 v143, v250
	v_cndmask_b32_e64 v143, v143, -v250, s[10:11]
	s_waitcnt vmcnt(1) lgkmcnt(0)
	v_mul_f32_e32 v143, v113, v143
	v_fma_f32 v142, v142, v112, v143
	v_mul_f32_e32 v143, v86, v139
	s_and_b64 vcc, exec, s[0:1]
	v_mul_f32_e32 v143, v22, v143
	s_cbranch_vccnz .LBB0_396
.LBB0_679:
	v_mov_b32_e32 v144, v143
	v_mov_b32_e32 v250, v143
	s_nop 1
	v_permlane32_swap_b32_e32 v144, v250
	v_cndmask_b32_e64 v144, v144, -v250, s[10:11]
	s_waitcnt vmcnt(2) lgkmcnt(0)
	v_mul_f32_e32 v144, v107, v144
	v_fma_f32 v143, v143, v106, v144
	v_mul_f32_e32 v144, v87, v139
	s_and_b64 vcc, exec, s[0:1]
	v_mul_f32_e32 v144, v23, v144
	s_cbranch_vccnz .LBB0_397
.LBB0_680:
	v_mov_b32_e32 v145, v144
	v_mov_b32_e32 v250, v144
	s_nop 1
	v_permlane32_swap_b32_e32 v145, v250
	v_cndmask_b32_e64 v145, v145, -v250, s[10:11]
	s_waitcnt vmcnt(2) lgkmcnt(0)
	v_mul_f32_e32 v145, v109, v145
	v_fma_f32 v144, v144, v108, v145
	v_mul_f32_e32 v145, v88, v139
	s_and_b64 vcc, exec, s[0:1]
	v_mul_f32_e32 v145, v24, v145
	s_cbranch_vccnz .LBB0_398
.LBB0_681:
	v_mov_b32_e32 v146, v145
	v_mov_b32_e32 v250, v145
	s_nop 1
	v_permlane32_swap_b32_e32 v146, v250
	v_cndmask_b32_e64 v146, v146, -v250, s[10:11]
	s_waitcnt vmcnt(3) lgkmcnt(0)
	v_mul_f32_e32 v146, v103, v146
	v_fma_f32 v145, v145, v102, v146
	v_mul_f32_e32 v139, v89, v139
	s_and_b64 vcc, exec, s[0:1]
	v_mul_f32_e32 v146, v25, v139
	s_cbranch_vccz .LBB0_399
	s_branch .LBB0_400

.LBB0_687:
	v_mov_b32_e32 v119, v0
	v_mov_b32_e32 v250, v0
	s_nop 1
	v_permlane32_swap_b32_e32 v119, v250
	v_cndmask_b32_e64 v119, v119, -v250, s[10:11]
	s_waitcnt vmcnt(0) lgkmcnt(0)
	v_mul_f32_e32 v119, v99, v119
	v_fma_f32 v0, v0, v98, v119
	v_mul_f32_e32 v119, v83, v125
	s_and_b64 vcc, exec, s[0:1]
	v_mul_f32_e32 v119, v39, v119
	s_cbranch_vccnz .LBB0_426
.LBB0_688:
	v_mov_b32_e32 v120, v119
	v_mov_b32_e32 v250, v119
	s_nop 1
	v_permlane32_swap_b32_e32 v120, v250
	v_cndmask_b32_e64 v120, v120, -v250, s[10:11]
	s_waitcnt vmcnt(0) lgkmcnt(0)
	v_mul_f32_e32 v120, v101, v120
	v_fma_f32 v119, v119, v100, v120
	v_mul_f32_e32 v120, v84, v125
	s_and_b64 vcc, exec, s[0:1]
	v_mul_f32_e32 v120, v40, v120
	s_cbranch_vccnz .LBB0_427
.LBB0_689:
	v_mov_b32_e32 v121, v120
	v_mov_b32_e32 v250, v120
	s_nop 1
	v_permlane32_swap_b32_e32 v121, v250
	v_cndmask_b32_e64 v121, v121, -v250, s[10:11]
	s_waitcnt vmcnt(1) lgkmcnt(0)
	v_mul_f32_e32 v121, v95, v121
	v_fma_f32 v120, v120, v94, v121
	v_mul_f32_e32 v121, v85, v125
	s_and_b64 vcc, exec, s[0:1]
	v_mul_f32_e32 v121, v41, v121
	s_cbranch_vccnz .LBB0_428
.LBB0_690:
	v_mov_b32_e32 v122, v121
	v_mov_b32_e32 v250, v121
	s_nop 1
	v_permlane32_swap_b32_e32 v122, v250
	v_cndmask_b32_e64 v122, v122, -v250, s[10:11]
	s_waitcnt vmcnt(1) lgkmcnt(0)
	v_mul_f32_e32 v122, v97, v122
	v_fma_f32 v121, v121, v96, v122
	v_mul_f32_e32 v122, v78, v125
	s_and_b64 vcc, exec, s[0:1]
	v_mul_f32_e32 v122, v34, v122
	s_cbranch_vccnz .LBB0_429
.LBB0_691:
	v_mov_b32_e32 v123, v122
	v_mov_b32_e32 v250, v122
	s_nop 1
	v_permlane32_swap_b32_e32 v123, v250
	v_cndmask_b32_e64 v123, v123, -v250, s[10:11]
	s_waitcnt vmcnt(2) lgkmcnt(0)
	v_mul_f32_e32 v123, v91, v123
	v_fma_f32 v122, v122, v90, v123
	v_mul_f32_e32 v123, v79, v125
	s_and_b64 vcc, exec, s[0:1]
	v_mul_f32_e32 v123, v35, v123
	s_cbranch_vccnz .LBB0_430
.LBB0_692:
	v_mov_b32_e32 v126, v123
	v_mov_b32_e32 v250, v123
	s_nop 1
	v_permlane32_swap_b32_e32 v126, v250
	v_cndmask_b32_e64 v126, v126, -v250, s[10:11]
	s_waitcnt vmcnt(2) lgkmcnt(0)
	v_mul_f32_e32 v126, v93, v126
	v_fma_f32 v123, v123, v92, v126
	v_mul_f32_e32 v126, v80, v125
	s_and_b64 vcc, exec, s[0:1]
	v_mul_f32_e32 v126, v36, v126
	s_cbranch_vccnz .LBB0_431
.LBB0_693:
	v_mov_b32_e32 v127, v126
	v_mov_b32_e32 v250, v126
	s_nop 1
	v_permlane32_swap_b32_e32 v127, v250
	v_cndmask_b32_e64 v127, v127, -v250, s[10:11]
	s_waitcnt vmcnt(3) lgkmcnt(0)
	v_mul_f32_e32 v127, v87, v127
	v_fma_f32 v126, v126, v86, v127
	v_mul_f32_e32 v127, v81, v125
	s_and_b64 vcc, exec, s[0:1]
	v_mul_f32_e32 v131, v37, v127
	s_cbranch_vccz .LBB0_432
	s_branch .LBB0_433

.LBB0_696:
	v_mov_b32_e32 v122, v0
	v_mov_b32_e32 v250, v0
	s_nop 1
	v_permlane32_swap_b32_e32 v122, v250
	v_cndmask_b32_e64 v122, v122, -v250, s[10:11]
	s_waitcnt vmcnt(0) lgkmcnt(0)
	v_mul_f32_e32 v122, v99, v122
	v_fma_f32 v0, v0, v98, v122
	v_mul_f32_e32 v122, v75, v125
	s_and_b64 vcc, exec, s[0:1]
	v_mul_f32_e32 v122, v27, v122
	s_cbranch_vccnz .LBB0_439
.LBB0_697:
	v_mov_b32_e32 v126, v122
	v_mov_b32_e32 v250, v122
	s_nop 1
	v_permlane32_swap_b32_e32 v126, v250
	v_cndmask_b32_e64 v126, v126, -v250, s[10:11]
	s_waitcnt vmcnt(0) lgkmcnt(0)
	v_mul_f32_e32 v126, v101, v126
	v_fma_f32 v122, v122, v100, v126
	v_mul_f32_e32 v126, v76, v125
	s_and_b64 vcc, exec, s[0:1]
	v_mul_f32_e32 v126, v28, v126
	s_cbranch_vccnz .LBB0_440
.LBB0_698:
	v_mov_b32_e32 v127, v126
	v_mov_b32_e32 v250, v126
	s_nop 1
	v_permlane32_swap_b32_e32 v127, v250
	v_cndmask_b32_e64 v127, v127, -v250, s[10:11]
	s_waitcnt vmcnt(1) lgkmcnt(0)
	v_mul_f32_e32 v127, v95, v127
	v_fma_f32 v126, v126, v94, v127
	v_mul_f32_e32 v127, v77, v125
	s_and_b64 vcc, exec, s[0:1]
	v_mul_f32_e32 v127, v29, v127
	s_cbranch_vccnz .LBB0_441
.LBB0_699:
	v_mov_b32_e32 v128, v127
	v_mov_b32_e32 v250, v127
	s_nop 1
	v_permlane32_swap_b32_e32 v128, v250
	v_cndmask_b32_e64 v128, v128, -v250, s[10:11]
	s_waitcnt vmcnt(1) lgkmcnt(0)
	v_mul_f32_e32 v128, v97, v128
	v_fma_f32 v127, v127, v96, v128
	v_mul_f32_e32 v128, v70, v125
	s_and_b64 vcc, exec, s[0:1]
	v_mul_f32_e32 v128, v22, v128
	s_cbranch_vccnz .LBB0_442
.LBB0_700:
	v_mov_b32_e32 v129, v128
	v_mov_b32_e32 v250, v128
	s_nop 1
	v_permlane32_swap_b32_e32 v129, v250
	v_cndmask_b32_e64 v129, v129, -v250, s[10:11]
	s_waitcnt vmcnt(2) lgkmcnt(0)
	v_mul_f32_e32 v129, v91, v129
	v_fma_f32 v128, v128, v90, v129
	v_mul_f32_e32 v129, v71, v125
	s_and_b64 vcc, exec, s[0:1]
	v_mul_f32_e32 v129, v23, v129
	s_cbranch_vccnz .LBB0_443
.LBB0_701:
	v_mov_b32_e32 v130, v129
	v_mov_b32_e32 v250, v129
	s_nop 1
	v_permlane32_swap_b32_e32 v130, v250
	v_cndmask_b32_e64 v130, v130, -v250, s[10:11]
	s_waitcnt vmcnt(2) lgkmcnt(0)
	v_mul_f32_e32 v130, v93, v130
	v_fma_f32 v129, v129, v92, v130
	v_mul_f32_e32 v130, v72, v125
	s_and_b64 vcc, exec, s[0:1]
	v_mul_f32_e32 v130, v24, v130
	s_cbranch_vccnz .LBB0_444

.LBB0_708:
	v_mov_b32_e32 v103, v0
	v_mov_b32_e32 v250, v0
	s_nop 1
	v_permlane32_swap_b32_e32 v103, v250
	v_cndmask_b32_e64 v103, v103, -v250, s[10:11]
	s_waitcnt vmcnt(0) lgkmcnt(0)
	v_mul_f32_e32 v103, v83, v103
	v_fma_f32 v0, v0, v82, v103
	v_mul_f32_e32 v103, v67, v109
	s_and_b64 vcc, exec, s[0:1]
	v_mul_f32_e32 v103, v39, v103
	s_cbranch_vccnz .LBB0_472
.LBB0_709:
	v_mov_b32_e32 v104, v103
	v_mov_b32_e32 v250, v103
	s_nop 1
	v_permlane32_swap_b32_e32 v104, v250
	v_cndmask_b32_e64 v104, v104, -v250, s[10:11]
	s_waitcnt vmcnt(0) lgkmcnt(0)
	v_mul_f32_e32 v104, v85, v104
	v_fma_f32 v103, v103, v84, v104
	v_mul_f32_e32 v104, v68, v109
	s_and_b64 vcc, exec, s[0:1]
	v_mul_f32_e32 v104, v40, v104
	s_cbranch_vccnz .LBB0_473
.LBB0_710:
	v_mov_b32_e32 v105, v104
	v_mov_b32_e32 v250, v104
	s_nop 1
	v_permlane32_swap_b32_e32 v105, v250
	v_cndmask_b32_e64 v105, v105, -v250, s[10:11]
	s_waitcnt vmcnt(1) lgkmcnt(0)
	v_mul_f32_e32 v105, v79, v105
	v_fma_f32 v104, v104, v78, v105
	v_mul_f32_e32 v105, v69, v109
	s_and_b64 vcc, exec, s[0:1]
	v_mul_f32_e32 v105, v41, v105
	s_cbranch_vccnz .LBB0_474
.LBB0_711:
	v_mov_b32_e32 v106, v105
	v_mov_b32_e32 v250, v105
	s_nop 1
	v_permlane32_swap_b32_e32 v106, v250
	v_cndmask_b32_e64 v106, v106, -v250, s[10:11]
	s_waitcnt vmcnt(1) lgkmcnt(0)
	v_mul_f32_e32 v106, v81, v106
	v_fma_f32 v105, v105, v80, v106
	v_mul_f32_e32 v106, v62, v109
	s_and_b64 vcc, exec, s[0:1]
	v_mul_f32_e32 v106, v34, v106
	s_cbranch_vccnz .LBB0_475
.LBB0_712:
	v_mov_b32_e32 v107, v106
	v_mov_b32_e32 v250, v106
	s_nop 1
	v_permlane32_swap_b32_e32 v107, v250
	v_cndmask_b32_e64 v107, v107, -v250, s[10:11]
	s_waitcnt vmcnt(2) lgkmcnt(0)
	v_mul_f32_e32 v107, v75, v107
	v_fma_f32 v106, v106, v74, v107
	v_mul_f32_e32 v107, v63, v109
	s_and_b64 vcc, exec, s[0:1]
	v_mul_f32_e32 v107, v35, v107
	s_cbranch_vccnz .LBB0_476
.LBB0_713:
	v_mov_b32_e32 v110, v107
	v_mov_b32_e32 v250, v107
	s_nop 1
	v_permlane32_swap_b32_e32 v110, v250
	v_cndmask_b32_e64 v110, v110, -v250, s[10:11]
	s_waitcnt vmcnt(2) lgkmcnt(0)
	v_mul_f32_e32 v110, v77, v110
	v_fma_f32 v107, v107, v76, v110
	v_mul_f32_e32 v110, v64, v109
	s_and_b64 vcc, exec, s[0:1]
	v_mul_f32_e32 v110, v36, v110
	s_cbranch_vccnz .LBB0_477
.LBB0_714:
	v_mov_b32_e32 v111, v110
	v_mov_b32_e32 v250, v110
	s_nop 1
	v_permlane32_swap_b32_e32 v111, v250
	v_cndmask_b32_e64 v111, v111, -v250, s[10:11]
	s_waitcnt vmcnt(3) lgkmcnt(0)
	v_mul_f32_e32 v111, v71, v111
	v_fma_f32 v110, v110, v70, v111
	v_mul_f32_e32 v111, v65, v109
	s_and_b64 vcc, exec, s[0:1]
	v_mul_f32_e32 v115, v37, v111
	s_cbranch_vccz .LBB0_478
	s_branch .LBB0_479

.LBB0_717:
	v_mov_b32_e32 v106, v0
	v_mov_b32_e32 v250, v0
	s_nop 1
	v_permlane32_swap_b32_e32 v106, v250
	v_cndmask_b32_e64 v106, v106, -v250, s[10:11]
	s_waitcnt vmcnt(0) lgkmcnt(0)
	v_mul_f32_e32 v106, v83, v106
	v_fma_f32 v0, v0, v82, v106
	v_mul_f32_e32 v106, v59, v109
	s_and_b64 vcc, exec, s[0:1]
	v_mul_f32_e32 v106, v27, v106
	s_cbranch_vccnz .LBB0_485
.LBB0_718:
	v_mov_b32_e32 v110, v106
	v_mov_b32_e32 v250, v106
	s_nop 1
	v_permlane32_swap_b32_e32 v110, v250
	v_cndmask_b32_e64 v110, v110, -v250, s[10:11]
	s_waitcnt vmcnt(0) lgkmcnt(0)
	v_mul_f32_e32 v110, v85, v110
	v_fma_f32 v106, v106, v84, v110
	v_mul_f32_e32 v110, v60, v109
	s_and_b64 vcc, exec, s[0:1]
	v_mul_f32_e32 v110, v28, v110
	s_cbranch_vccnz .LBB0_486
.LBB0_719:
	v_mov_b32_e32 v111, v110
	v_mov_b32_e32 v250, v110
	s_nop 1
	v_permlane32_swap_b32_e32 v111, v250
	v_cndmask_b32_e64 v111, v111, -v250, s[10:11]
	s_waitcnt vmcnt(1) lgkmcnt(0)
	v_mul_f32_e32 v111, v79, v111
	v_fma_f32 v110, v110, v78, v111
	v_mul_f32_e32 v111, v61, v109
	s_and_b64 vcc, exec, s[0:1]
	v_mul_f32_e32 v111, v29, v111
	s_cbranch_vccnz .LBB0_487
.LBB0_720:
	v_mov_b32_e32 v112, v111
	v_mov_b32_e32 v250, v111
	s_nop 1
	v_permlane32_swap_b32_e32 v112, v250
	v_cndmask_b32_e64 v112, v112, -v250, s[10:11]
	s_waitcnt vmcnt(1) lgkmcnt(0)
	v_mul_f32_e32 v112, v81, v112
	v_fma_f32 v111, v111, v80, v112
	v_mul_f32_e32 v112, v54, v109
	s_and_b64 vcc, exec, s[0:1]
	v_mul_f32_e32 v112, v22, v112
	s_cbranch_vccnz .LBB0_488
.LBB0_721:
	v_mov_b32_e32 v113, v112
	v_mov_b32_e32 v250, v112
	s_nop 1
	v_permlane32_swap_b32_e32 v113, v250
	v_cndmask_b32_e64 v113, v113, -v250, s[10:11]
	s_waitcnt vmcnt(2) lgkmcnt(0)
	v_mul_f32_e32 v113, v75, v113
	v_fma_f32 v112, v112, v74, v113
	v_mul_f32_e32 v113, v55, v109
	s_and_b64 vcc, exec, s[0:1]
	v_mul_f32_e32 v113, v23, v113
	s_cbranch_vccnz .LBB0_489
.LBB0_722:
	v_mov_b32_e32 v114, v113
	v_mov_b32_e32 v250, v113
	s_nop 1
	v_permlane32_swap_b32_e32 v114, v250
	v_cndmask_b32_e64 v114, v114, -v250, s[10:11]
	s_waitcnt vmcnt(2) lgkmcnt(0)
	v_mul_f32_e32 v114, v77, v114
	v_fma_f32 v113, v113, v76, v114
	v_mul_f32_e32 v114, v56, v109
	s_and_b64 vcc, exec, s[0:1]
	v_mul_f32_e32 v114, v24, v114
	s_cbranch_vccnz .LBB0_490

.LBB0_729:
	v_mov_b32_e32 v87, v0
	v_mov_b32_e32 v250, v0
	s_nop 1
	v_permlane32_swap_b32_e32 v87, v250
	v_cndmask_b32_e64 v87, v87, -v250, s[10:11]
	s_waitcnt vmcnt(0) lgkmcnt(0)
	v_mul_f32_e32 v87, v67, v87
	v_fma_f32 v0, v0, v66, v87
	v_mul_f32_e32 v87, v51, v93
	s_and_b64 vcc, exec, s[0:1]
	v_mul_f32_e32 v87, v39, v87
	s_cbranch_vccnz .LBB0_518
.LBB0_730:
	v_mov_b32_e32 v88, v87
	v_mov_b32_e32 v250, v87
	s_nop 1
	v_permlane32_swap_b32_e32 v88, v250
	v_cndmask_b32_e64 v88, v88, -v250, s[10:11]
	s_waitcnt vmcnt(0) lgkmcnt(0)
	v_mul_f32_e32 v88, v69, v88
	v_fma_f32 v87, v87, v68, v88
	v_mul_f32_e32 v88, v52, v93
	s_and_b64 vcc, exec, s[0:1]
	v_mul_f32_e32 v88, v40, v88
	s_cbranch_vccnz .LBB0_519
.LBB0_731:
	v_mov_b32_e32 v89, v88
	v_mov_b32_e32 v250, v88
	s_nop 1
	v_permlane32_swap_b32_e32 v89, v250
	v_cndmask_b32_e64 v89, v89, -v250, s[10:11]
	s_waitcnt vmcnt(1) lgkmcnt(0)
	v_mul_f32_e32 v89, v63, v89
	v_fma_f32 v88, v88, v62, v89
	v_mul_f32_e32 v89, v53, v93
	s_and_b64 vcc, exec, s[0:1]
	v_mul_f32_e32 v89, v41, v89
	s_cbranch_vccnz .LBB0_520
.LBB0_732:
	v_mov_b32_e32 v90, v89
	v_mov_b32_e32 v250, v89
	s_nop 1
	v_permlane32_swap_b32_e32 v90, v250
	v_cndmask_b32_e64 v90, v90, -v250, s[10:11]
	s_waitcnt vmcnt(1) lgkmcnt(0)
	v_mul_f32_e32 v90, v65, v90
	v_fma_f32 v89, v89, v64, v90
	v_mul_f32_e32 v90, v46, v93
	s_and_b64 vcc, exec, s[0:1]
	v_mul_f32_e32 v90, v34, v90
	s_cbranch_vccnz .LBB0_521
.LBB0_733:
	v_mov_b32_e32 v91, v90
	v_mov_b32_e32 v250, v90
	s_nop 1
	v_permlane32_swap_b32_e32 v91, v250
	v_cndmask_b32_e64 v91, v91, -v250, s[10:11]
	s_waitcnt vmcnt(2) lgkmcnt(0)
	v_mul_f32_e32 v91, v59, v91
	v_fma_f32 v90, v90, v58, v91
	v_mul_f32_e32 v91, v47, v93
	s_and_b64 vcc, exec, s[0:1]
	v_mul_f32_e32 v91, v35, v91
	s_cbranch_vccnz .LBB0_522
.LBB0_734:
	v_mov_b32_e32 v94, v91
	v_mov_b32_e32 v250, v91
	s_nop 1
	v_permlane32_swap_b32_e32 v94, v250
	v_cndmask_b32_e64 v94, v94, -v250, s[10:11]
	s_waitcnt vmcnt(2) lgkmcnt(0)
	v_mul_f32_e32 v94, v61, v94
	v_fma_f32 v91, v91, v60, v94
	v_mul_f32_e32 v94, v48, v93
	s_and_b64 vcc, exec, s[0:1]
	v_mul_f32_e32 v94, v36, v94
	s_cbranch_vccnz .LBB0_523
.LBB0_735:
	v_mov_b32_e32 v95, v94
	v_mov_b32_e32 v250, v94
	s_nop 1
	v_permlane32_swap_b32_e32 v95, v250
	v_cndmask_b32_e64 v95, v95, -v250, s[10:11]
	s_waitcnt vmcnt(3) lgkmcnt(0)
	v_mul_f32_e32 v95, v55, v95
	v_fma_f32 v94, v94, v54, v95
	v_mul_f32_e32 v95, v49, v93
	s_and_b64 vcc, exec, s[0:1]
	v_mul_f32_e32 v99, v37, v95
	s_cbranch_vccz .LBB0_524
	s_branch .LBB0_525

.LBB0_738:
	v_mov_b32_e32 v90, v0
	v_mov_b32_e32 v250, v0
	s_nop 1
	v_permlane32_swap_b32_e32 v90, v250
	v_cndmask_b32_e64 v90, v90, -v250, s[10:11]
	s_waitcnt vmcnt(0) lgkmcnt(0)
	v_mul_f32_e32 v90, v67, v90
	v_fma_f32 v0, v0, v66, v90
	v_mul_f32_e32 v90, v43, v93
	s_and_b64 vcc, exec, s[0:1]
	v_mul_f32_e32 v90, v27, v90
	s_cbranch_vccnz .LBB0_531
.LBB0_739:
	v_mov_b32_e32 v94, v90
	v_mov_b32_e32 v250, v90
	s_nop 1
	v_permlane32_swap_b32_e32 v94, v250
	v_cndmask_b32_e64 v94, v94, -v250, s[10:11]
	s_waitcnt vmcnt(0) lgkmcnt(0)
	v_mul_f32_e32 v94, v69, v94
	v_fma_f32 v90, v90, v68, v94
	v_mul_f32_e32 v94, v44, v93
	s_and_b64 vcc, exec, s[0:1]
	v_mul_f32_e32 v94, v28, v94
	s_cbranch_vccnz .LBB0_532
.LBB0_740:
	v_mov_b32_e32 v95, v94
	v_mov_b32_e32 v250, v94
	s_nop 1
	v_permlane32_swap_b32_e32 v95, v250
	v_cndmask_b32_e64 v95, v95, -v250, s[10:11]
	s_waitcnt vmcnt(1) lgkmcnt(0)
	v_mul_f32_e32 v95, v63, v95
	v_fma_f32 v94, v94, v62, v95
	v_mul_f32_e32 v95, v45, v93
	s_and_b64 vcc, exec, s[0:1]
	v_mul_f32_e32 v95, v29, v95
	s_cbranch_vccnz .LBB0_533
.LBB0_741:
	v_mov_b32_e32 v96, v95
	v_mov_b32_e32 v250, v95
	s_nop 1
	v_permlane32_swap_b32_e32 v96, v250
	v_cndmask_b32_e64 v96, v96, -v250, s[10:11]
	s_waitcnt vmcnt(1) lgkmcnt(0)
	v_mul_f32_e32 v96, v65, v96
	v_fma_f32 v95, v95, v64, v96
	v_mul_f32_e32 v96, v30, v93
	s_and_b64 vcc, exec, s[0:1]
	v_mul_f32_e32 v96, v22, v96
	s_cbranch_vccnz .LBB0_534
.LBB0_742:
	v_mov_b32_e32 v97, v96
	v_mov_b32_e32 v250, v96
	s_nop 1
	v_permlane32_swap_b32_e32 v97, v250
	v_cndmask_b32_e64 v97, v97, -v250, s[10:11]
	s_waitcnt vmcnt(2) lgkmcnt(0)
	v_mul_f32_e32 v97, v59, v97
	v_fma_f32 v96, v96, v58, v97
	v_mul_f32_e32 v97, v31, v93
	s_and_b64 vcc, exec, s[0:1]
	v_mul_f32_e32 v97, v23, v97
	s_cbranch_vccnz .LBB0_535
.LBB0_743:
	v_mov_b32_e32 v98, v97
	v_mov_b32_e32 v250, v97
	s_nop 1
	v_permlane32_swap_b32_e32 v98, v250
	v_cndmask_b32_e64 v98, v98, -v250, s[10:11]
	s_waitcnt vmcnt(2) lgkmcnt(0)
	v_mul_f32_e32 v98, v61, v98
	v_fma_f32 v97, v97, v60, v98
	v_mul_f32_e32 v98, v32, v93
	s_and_b64 vcc, exec, s[0:1]
	v_mul_f32_e32 v98, v24, v98
	s_cbranch_vccnz .LBB0_536

.LBB0_750:
	v_mov_b32_e32 v31, v0
	v_mov_b32_e32 v250, v0
	s_nop 1
	v_permlane32_swap_b32_e32 v31, v250
	v_cndmask_b32_e64 v31, v31, -v250, s[10:11]
	s_waitcnt vmcnt(0) lgkmcnt(0)
	v_mul_f32_e32 v31, v67, v31
	v_fma_f32 v0, v0, v66, v31
	v_mul_f32_e32 v31, v19, v43
	s_and_b64 vcc, exec, s[0:1]
	v_mul_f32_e32 v31, v39, v31
	s_cbranch_vccnz .LBB0_569
.LBB0_751:
	v_mov_b32_e32 v32, v31
	v_mov_b32_e32 v250, v31
	s_nop 1
	v_permlane32_swap_b32_e32 v32, v250
	v_cndmask_b32_e64 v32, v32, -v250, s[10:11]
	s_waitcnt vmcnt(0) lgkmcnt(0)
	v_mul_f32_e32 v32, v69, v32
	v_fma_f32 v31, v31, v68, v32
	v_mul_f32_e32 v32, v20, v43
	s_and_b64 vcc, exec, s[0:1]
	v_mul_f32_e32 v32, v40, v32
	s_cbranch_vccnz .LBB0_570
.LBB0_752:
	v_mov_b32_e32 v33, v32
	v_mov_b32_e32 v250, v32
	s_nop 1
	v_permlane32_swap_b32_e32 v33, v250
	v_cndmask_b32_e64 v33, v33, -v250, s[10:11]
	s_waitcnt vmcnt(1) lgkmcnt(0)
	v_mul_f32_e32 v33, v63, v33
	v_fma_f32 v32, v32, v62, v33
	v_mul_f32_e32 v33, v21, v43
	s_and_b64 vcc, exec, s[0:1]
	v_mul_f32_e32 v33, v41, v33
	s_cbranch_vccnz .LBB0_571
.LBB0_753:
	v_mov_b32_e32 v38, v33
	v_mov_b32_e32 v250, v33
	s_nop 1
	v_permlane32_swap_b32_e32 v38, v250
	v_cndmask_b32_e64 v38, v38, -v250, s[10:11]
	s_waitcnt vmcnt(1) lgkmcnt(0)
	v_mul_f32_e32 v38, v65, v38
	v_fma_f32 v33, v33, v64, v38
	v_mul_f32_e32 v38, v14, v43
	s_and_b64 vcc, exec, s[0:1]
	v_mul_f32_e32 v34, v34, v38
	s_cbranch_vccnz .LBB0_572
.LBB0_754:
	v_mov_b32_e32 v38, v34
	v_mov_b32_e32 v250, v34
	s_nop 1
	v_permlane32_swap_b32_e32 v38, v250
	v_cndmask_b32_e64 v38, v38, -v250, s[10:11]
	s_waitcnt vmcnt(2) lgkmcnt(0)
	v_mul_f32_e32 v38, v59, v38
	v_fma_f32 v34, v34, v58, v38
	v_mul_f32_e32 v38, v15, v43
	s_and_b64 vcc, exec, s[0:1]
	v_mul_f32_e32 v35, v35, v38
	s_cbranch_vccnz .LBB0_573
.LBB0_755:
	v_mov_b32_e32 v38, v35
	v_mov_b32_e32 v250, v35
	s_nop 1
	v_permlane32_swap_b32_e32 v38, v250
	v_cndmask_b32_e64 v38, v38, -v250, s[10:11]
	s_waitcnt vmcnt(2) lgkmcnt(0)
	v_mul_f32_e32 v38, v61, v38
	v_fma_f32 v35, v35, v60, v38
	v_mul_f32_e32 v38, v16, v43
	s_and_b64 vcc, exec, s[0:1]
	v_mul_f32_e32 v36, v36, v38
	s_cbranch_vccnz .LBB0_574
.LBB0_756:
	v_mov_b32_e32 v38, v36
	v_mov_b32_e32 v250, v36
	s_nop 1
	v_permlane32_swap_b32_e32 v38, v250
	v_cndmask_b32_e64 v38, v38, -v250, s[10:11]
	s_waitcnt vmcnt(3) lgkmcnt(0)
	v_mul_f32_e32 v38, v55, v38
	v_fma_f32 v36, v36, v54, v38
	v_mul_f32_e32 v38, v17, v43
	s_and_b64 vcc, exec, s[0:1]
	v_mul_f32_e32 v41, v37, v38
	s_cbranch_vccz .LBB0_575
	s_branch .LBB0_576

.LBB0_759:
	v_mov_b32_e32 v34, v26
	v_mov_b32_e32 v250, v26
	s_nop 1
	v_permlane32_swap_b32_e32 v34, v250
	v_cndmask_b32_e64 v34, v34, -v250, s[10:11]
	s_waitcnt vmcnt(0) lgkmcnt(0)
	v_mul_f32_e32 v34, v67, v34
	v_fma_f32 v26, v26, v66, v34
	v_mul_f32_e32 v34, v11, v43
	s_and_b64 vcc, exec, s[0:1]
	v_mul_f32_e32 v27, v27, v34
	s_cbranch_vccnz .LBB0_582
.LBB0_760:
	v_mov_b32_e32 v34, v27
	v_mov_b32_e32 v250, v27
	s_nop 1
	v_permlane32_swap_b32_e32 v34, v250
	v_cndmask_b32_e64 v34, v34, -v250, s[10:11]
	s_waitcnt vmcnt(0) lgkmcnt(0)
	v_mul_f32_e32 v34, v69, v34
	v_fma_f32 v27, v27, v68, v34
	v_mul_f32_e32 v34, v12, v43
	s_and_b64 vcc, exec, s[0:1]
	v_mul_f32_e32 v28, v28, v34
	s_cbranch_vccnz .LBB0_583
.LBB0_761:
	v_mov_b32_e32 v34, v28
	v_mov_b32_e32 v250, v28
	s_nop 1
	v_permlane32_swap_b32_e32 v34, v250
	v_cndmask_b32_e64 v34, v34, -v250, s[10:11]
	s_waitcnt vmcnt(1) lgkmcnt(0)
	v_mul_f32_e32 v34, v63, v34
	v_fma_f32 v28, v28, v62, v34
	v_mul_f32_e32 v34, v13, v43
	s_and_b64 vcc, exec, s[0:1]
	v_mul_f32_e32 v29, v29, v34
	s_cbranch_vccnz .LBB0_584
.LBB0_762:
	v_mov_b32_e32 v34, v29
	v_mov_b32_e32 v250, v29
	s_nop 1
	v_permlane32_swap_b32_e32 v34, v250
	v_cndmask_b32_e64 v34, v34, -v250, s[10:11]
	s_waitcnt vmcnt(1) lgkmcnt(0)
	v_mul_f32_e32 v34, v65, v34
	v_fma_f32 v29, v29, v64, v34
	v_mul_f32_e32 v34, v6, v43
	s_and_b64 vcc, exec, s[0:1]
	v_mul_f32_e32 v22, v22, v34
	s_cbranch_vccnz .LBB0_585
.LBB0_763:
	v_mov_b32_e32 v34, v22
	v_mov_b32_e32 v250, v22
	s_nop 1
	v_permlane32_swap_b32_e32 v34, v250
	v_cndmask_b32_e64 v34, v34, -v250, s[10:11]
	s_waitcnt vmcnt(2) lgkmcnt(0)
	v_mul_f32_e32 v34, v59, v34
	v_fma_f32 v22, v22, v58, v34
	v_mul_f32_e32 v34, v7, v43
	s_and_b64 vcc, exec, s[0:1]
	v_mul_f32_e32 v34, v23, v34
	s_cbranch_vccnz .LBB0_586
.LBB0_764:
	v_mov_b32_e32 v23, v34
	v_mov_b32_e32 v250, v34
	s_nop 1
	v_permlane32_swap_b32_e32 v23, v250
	v_cndmask_b32_e64 v23, v23, -v250, s[10:11]
	s_waitcnt vmcnt(2) lgkmcnt(0)
	v_mul_f32_e32 v23, v61, v23
	v_fma_f32 v34, v34, v60, v23
	v_mul_f32_e32 v23, v8, v43
	s_and_b64 vcc, exec, s[0:1]
	v_mul_f32_e32 v23, v24, v23
	s_cbranch_vccnz .LBB0_587
.LBB0_765:
	v_mov_b32_e32 v24, v23
	v_mov_b32_e32 v250, v23
	s_nop 1
	v_permlane32_swap_b32_e32 v24, v250
	v_cndmask_b32_e64 v24, v24, -v250, s[10:11]
	s_waitcnt vmcnt(3) lgkmcnt(0)
	v_mul_f32_e32 v24, v55, v24
	v_fma_f32 v23, v23, v54, v24
	v_mul_f32_e32 v24, v9, v43
	s_and_b64 vcc, exec, s[0:1]
	v_mul_f32_e32 v25, v25, v24
	s_cbranch_vccz .LBB0_588
	s_branch .LBB0_589
